# v009 + hand-written P8 SwiGLU epilogue (scalar f32 VALU on the accumulators in place, no v_pk_mul/v_mov shuffles), widened stores kept
# speedup vs baseline: 1.0063x; 1.0063x over previous
.LBB0_893:
	v_lshl_add_u32 v146, s26, 8, v154
	v_ashrrev_i32_e32 v147, 31, v146
	v_lshl_add_u64 v[144:145], v[146:147], 2, s[12:13]
	global_load_dword v170, v[144:145], off
	global_load_dword v171, v[144:145], off offset:64
	global_load_dword v172, v[144:145], off offset:128
	global_load_dword v173, v[144:145], off offset:192
	global_load_dword v174, v[144:145], off offset:512
	global_load_dword v175, v[144:145], off offset:576
	global_load_dword v176, v[144:145], off offset:640
	global_load_dword v177, v[144:145], off offset:704
	s_waitcnt vmcnt(0)
	v_lshl_or_b32 v147, s55, 8, v156
	v_mov_b64_e32 v[144:145], s[10:11]
	v_mad_i64_i32 v[166:167], s[28:29], v146, s54, v[144:145]
	v_ashrrev_i32_e32 v146, 1, v147
	v_ashrrev_i32_e32 v147, 31, v146
	v_lshlrev_b64 v[146:147], 1, v[146:147]
	v_lshl_add_u64 v[166:167], v[166:167], 0, v[146:147]
	s_andn2_b64 vcc, exec, s[2:3]
	s_mov_b64 s[2:3], -1
	v_fmamk_f32 v162, v170, 0x3a800000, v160
	v_rsq_f32_e32 v162, v162
	s_nop 0
	v_mul_f32_e32 v163, 0xbfb8aa3b, v162
	v_mul_f32_e32 v164, v162, v162
	v_mul_f32_e32 v144, v163, v124
	v_mul_f32_e32 v145, v163, v126
	v_mul_f32_e32 v146, v163, v120
	v_mul_f32_e32 v147, v163, v122
	v_exp_f32_e32 v144, v144
	v_exp_f32_e32 v145, v145
	v_exp_f32_e32 v146, v146
	v_exp_f32_e32 v147, v147
	v_mul_f32_e32 v148, v124, v125
	v_mul_f32_e32 v149, v126, v127
	v_mul_f32_e32 v150, v120, v121
	v_mul_f32_e32 v151, v122, v123
	v_add_f32_e32 v144, 1.0, v144
	v_add_f32_e32 v145, 1.0, v145
	v_add_f32_e32 v146, 1.0, v146
	v_add_f32_e32 v147, 1.0, v147
	v_rcp_f32_e32 v144, v144
	v_rcp_f32_e32 v145, v145
	v_rcp_f32_e32 v146, v146
	v_rcp_f32_e32 v147, v147
	v_mul_f32_e32 v148, v164, v148
	v_mul_f32_e32 v149, v164, v149
	v_mul_f32_e32 v150, v164, v150
	v_mul_f32_e32 v151, v164, v151
	v_mul_f32_e32 v148, v148, v144
	v_mul_f32_e32 v149, v149, v145
	v_mul_f32_e32 v150, v150, v146
	v_mul_f32_e32 v151, v151, v147
	v_cvt_pk_bf16_f32 v186, v148, v149
	v_cvt_pk_bf16_f32 v187, v150, v151
	v_mul_f32_e32 v178, v163, v116
	v_mul_f32_e32 v179, v163, v118
	v_mul_f32_e32 v180, v163, v112
	v_mul_f32_e32 v181, v163, v114
	v_exp_f32_e32 v178, v178
	v_exp_f32_e32 v179, v179
	v_exp_f32_e32 v180, v180
	v_exp_f32_e32 v181, v181
	v_mul_f32_e32 v182, v116, v117
	v_mul_f32_e32 v183, v118, v119
	v_mul_f32_e32 v184, v112, v113
	v_mul_f32_e32 v185, v114, v115
	v_add_f32_e32 v178, 1.0, v178
	v_add_f32_e32 v179, 1.0, v179
	v_add_f32_e32 v180, 1.0, v180
	v_add_f32_e32 v181, 1.0, v181
	v_rcp_f32_e32 v178, v178
	v_rcp_f32_e32 v179, v179
	v_rcp_f32_e32 v180, v180
	v_rcp_f32_e32 v181, v181
	v_mul_f32_e32 v182, v164, v182
	v_mul_f32_e32 v183, v164, v183
	v_mul_f32_e32 v184, v164, v184
	v_mul_f32_e32 v185, v164, v185
	v_mul_f32_e32 v182, v182, v178
	v_mul_f32_e32 v183, v183, v179
	v_mul_f32_e32 v184, v184, v180
	v_mul_f32_e32 v185, v185, v181
	v_cvt_pk_bf16_f32 v190, v182, v183
	v_cvt_pk_bf16_f32 v191, v184, v185
	v_fmamk_f32 v162, v171, 0x3a800000, v160
	v_rsq_f32_e32 v162, v162
	s_nop 0
	v_mul_f32_e32 v163, 0xbfb8aa3b, v162
	v_mul_f32_e32 v164, v162, v162
	v_mul_f32_e32 v144, v163, v108
	v_mul_f32_e32 v145, v163, v110
	v_mul_f32_e32 v146, v163, v104
	v_mul_f32_e32 v147, v163, v106
	v_exp_f32_e32 v144, v144
	v_exp_f32_e32 v145, v145
	v_exp_f32_e32 v146, v146
	v_exp_f32_e32 v147, v147
	v_mul_f32_e32 v148, v108, v109
	v_mul_f32_e32 v149, v110, v111
	v_mul_f32_e32 v150, v104, v105
	v_mul_f32_e32 v151, v106, v107
	v_add_f32_e32 v144, 1.0, v144
	v_add_f32_e32 v145, 1.0, v145
	v_add_f32_e32 v146, 1.0, v146
	v_add_f32_e32 v147, 1.0, v147
	v_rcp_f32_e32 v144, v144
	v_rcp_f32_e32 v145, v145
	v_rcp_f32_e32 v146, v146
	v_rcp_f32_e32 v147, v147
	v_mul_f32_e32 v148, v164, v148
	v_mul_f32_e32 v149, v164, v149
	v_mul_f32_e32 v150, v164, v150
	v_mul_f32_e32 v151, v164, v151
	v_mul_f32_e32 v148, v148, v144
	v_mul_f32_e32 v149, v149, v145
	v_mul_f32_e32 v150, v150, v146
	v_mul_f32_e32 v151, v151, v147
	v_cvt_pk_bf16_f32 v188, v148, v149
	v_cvt_pk_bf16_f32 v189, v150, v151
	v_mul_f32_e32 v178, v163, v100
	v_mul_f32_e32 v179, v163, v102
	v_mul_f32_e32 v180, v163, v96
	v_mul_f32_e32 v181, v163, v98
	v_exp_f32_e32 v178, v178
	v_exp_f32_e32 v179, v179
	v_exp_f32_e32 v180, v180
	v_exp_f32_e32 v181, v181
	v_mul_f32_e32 v182, v100, v101
	v_mul_f32_e32 v183, v102, v103
	v_mul_f32_e32 v184, v96, v97
	v_mul_f32_e32 v185, v98, v99
	v_add_f32_e32 v178, 1.0, v178
	v_add_f32_e32 v179, 1.0, v179
	v_add_f32_e32 v180, 1.0, v180
	v_add_f32_e32 v181, 1.0, v181
	v_rcp_f32_e32 v178, v178
	v_rcp_f32_e32 v179, v179
	v_rcp_f32_e32 v180, v180
	v_rcp_f32_e32 v181, v181
	v_mul_f32_e32 v182, v164, v182
	v_mul_f32_e32 v183, v164, v183
	v_mul_f32_e32 v184, v164, v184
	v_mul_f32_e32 v185, v164, v185
	v_mul_f32_e32 v182, v182, v178
	v_mul_f32_e32 v183, v183, v179
	v_mul_f32_e32 v184, v184, v180
	v_mul_f32_e32 v185, v185, v181
	v_cvt_pk_bf16_f32 v192, v182, v183
	v_cvt_pk_bf16_f32 v193, v184, v185
	v_fmamk_f32 v162, v172, 0x3a800000, v160
	v_rsq_f32_e32 v162, v162
	s_nop 0
	v_mul_f32_e32 v163, 0xbfb8aa3b, v162
	v_mul_f32_e32 v164, v162, v162
	v_mul_f32_e32 v144, v163, v92
	v_mul_f32_e32 v145, v163, v94
	v_mul_f32_e32 v146, v163, v88
	v_mul_f32_e32 v147, v163, v90
	v_exp_f32_e32 v144, v144
	v_exp_f32_e32 v145, v145
	v_exp_f32_e32 v146, v146
	v_exp_f32_e32 v147, v147
	v_mul_f32_e32 v148, v92, v93
	v_mul_f32_e32 v149, v94, v95
	v_mul_f32_e32 v150, v88, v89
	v_mul_f32_e32 v151, v90, v91
	v_add_f32_e32 v144, 1.0, v144
	v_add_f32_e32 v145, 1.0, v145
	v_add_f32_e32 v146, 1.0, v146
	v_add_f32_e32 v147, 1.0, v147
	v_rcp_f32_e32 v144, v144
	v_rcp_f32_e32 v145, v145
	v_rcp_f32_e32 v146, v146
	v_rcp_f32_e32 v147, v147
	v_mul_f32_e32 v148, v164, v148
	v_mul_f32_e32 v149, v164, v149
	v_mul_f32_e32 v150, v164, v150
	v_mul_f32_e32 v151, v164, v151
	v_mul_f32_e32 v148, v148, v144
	v_mul_f32_e32 v149, v149, v145
	v_mul_f32_e32 v150, v150, v146
	v_mul_f32_e32 v151, v151, v147
	v_cvt_pk_bf16_f32 v194, v148, v149
	v_cvt_pk_bf16_f32 v195, v150, v151
	v_mul_f32_e32 v178, v163, v84
	v_mul_f32_e32 v179, v163, v86
	v_mul_f32_e32 v180, v163, v80
	v_mul_f32_e32 v181, v163, v82
	v_exp_f32_e32 v178, v178
	v_exp_f32_e32 v179, v179
	v_exp_f32_e32 v180, v180
	v_exp_f32_e32 v181, v181
	v_mul_f32_e32 v182, v84, v85
	v_mul_f32_e32 v183, v86, v87
	v_mul_f32_e32 v184, v80, v81
	v_mul_f32_e32 v185, v82, v83
	v_add_f32_e32 v178, 1.0, v178
	v_add_f32_e32 v179, 1.0, v179
	v_add_f32_e32 v180, 1.0, v180
	v_add_f32_e32 v181, 1.0, v181
	v_rcp_f32_e32 v178, v178
	v_rcp_f32_e32 v179, v179
	v_rcp_f32_e32 v180, v180
	v_rcp_f32_e32 v181, v181
	v_mul_f32_e32 v182, v164, v182
	v_mul_f32_e32 v183, v164, v183
	v_mul_f32_e32 v184, v164, v184
	v_mul_f32_e32 v185, v164, v185
	v_mul_f32_e32 v182, v182, v178
	v_mul_f32_e32 v183, v183, v179
	v_mul_f32_e32 v184, v184, v180
	v_mul_f32_e32 v185, v185, v181
	v_cvt_pk_bf16_f32 v198, v182, v183
	v_cvt_pk_bf16_f32 v199, v184, v185
	v_fmamk_f32 v162, v173, 0x3a800000, v160
	v_rsq_f32_e32 v162, v162
	s_nop 0
	v_mul_f32_e32 v163, 0xbfb8aa3b, v162
	v_mul_f32_e32 v164, v162, v162
	v_mul_f32_e32 v144, v163, v76
	v_mul_f32_e32 v145, v163, v78
	v_mul_f32_e32 v146, v163, v72
	v_mul_f32_e32 v147, v163, v74
	v_exp_f32_e32 v144, v144
	v_exp_f32_e32 v145, v145
	v_exp_f32_e32 v146, v146
	v_exp_f32_e32 v147, v147
	v_mul_f32_e32 v148, v76, v77
	v_mul_f32_e32 v149, v78, v79
	v_mul_f32_e32 v150, v72, v73
	v_mul_f32_e32 v151, v74, v75
	v_add_f32_e32 v144, 1.0, v144
	v_add_f32_e32 v145, 1.0, v145
	v_add_f32_e32 v146, 1.0, v146
	v_add_f32_e32 v147, 1.0, v147
	v_rcp_f32_e32 v144, v144
	v_rcp_f32_e32 v145, v145
	v_rcp_f32_e32 v146, v146
	v_rcp_f32_e32 v147, v147
	v_mul_f32_e32 v148, v164, v148
	v_mul_f32_e32 v149, v164, v149
	v_mul_f32_e32 v150, v164, v150
	v_mul_f32_e32 v151, v164, v151
	v_mul_f32_e32 v148, v148, v144
	v_mul_f32_e32 v149, v149, v145
	v_mul_f32_e32 v150, v150, v146
	v_mul_f32_e32 v151, v151, v147
	v_cvt_pk_bf16_f32 v196, v148, v149
	v_cvt_pk_bf16_f32 v197, v150, v151
	v_mul_f32_e32 v178, v163, v68
	v_mul_f32_e32 v179, v163, v70
	v_mul_f32_e32 v180, v163, v64
	v_mul_f32_e32 v181, v163, v66
	v_exp_f32_e32 v178, v178
	v_exp_f32_e32 v179, v179
	v_exp_f32_e32 v180, v180
	v_exp_f32_e32 v181, v181
	v_mul_f32_e32 v182, v68, v69
	v_mul_f32_e32 v183, v70, v71
	v_mul_f32_e32 v184, v64, v65
	v_mul_f32_e32 v185, v66, v67
	v_add_f32_e32 v178, 1.0, v178
	v_add_f32_e32 v179, 1.0, v179
	v_add_f32_e32 v180, 1.0, v180
	v_add_f32_e32 v181, 1.0, v181
	v_rcp_f32_e32 v178, v178
	v_rcp_f32_e32 v179, v179
	v_rcp_f32_e32 v180, v180
	v_rcp_f32_e32 v181, v181
	v_mul_f32_e32 v182, v164, v182
	v_mul_f32_e32 v183, v164, v183
	v_mul_f32_e32 v184, v164, v184
	v_mul_f32_e32 v185, v164, v185
	v_mul_f32_e32 v182, v182, v178
	v_mul_f32_e32 v183, v183, v179
	v_mul_f32_e32 v184, v184, v180
	v_mul_f32_e32 v185, v185, v181
	v_cvt_pk_bf16_f32 v200, v182, v183
	v_cvt_pk_bf16_f32 v201, v184, v185
	v_fmamk_f32 v162, v174, 0x3a800000, v160
	v_rsq_f32_e32 v162, v162
	s_nop 0
	v_mul_f32_e32 v163, 0xbfb8aa3b, v162
	v_mul_f32_e32 v164, v162, v162
	v_mul_f32_e32 v144, v163, v60
	v_mul_f32_e32 v145, v163, v62
	v_mul_f32_e32 v146, v163, v56
	v_mul_f32_e32 v147, v163, v58
	v_exp_f32_e32 v144, v144
	v_exp_f32_e32 v145, v145
	v_exp_f32_e32 v146, v146
	v_exp_f32_e32 v147, v147
	v_mul_f32_e32 v148, v60, v61
	v_mul_f32_e32 v149, v62, v63
	v_mul_f32_e32 v150, v56, v57
	v_mul_f32_e32 v151, v58, v59
	v_add_f32_e32 v144, 1.0, v144
	v_add_f32_e32 v145, 1.0, v145
	v_add_f32_e32 v146, 1.0, v146
	v_add_f32_e32 v147, 1.0, v147
	v_rcp_f32_e32 v144, v144
	v_rcp_f32_e32 v145, v145
	v_rcp_f32_e32 v146, v146
	v_rcp_f32_e32 v147, v147
	v_mul_f32_e32 v148, v164, v148
	v_mul_f32_e32 v149, v164, v149
	v_mul_f32_e32 v150, v164, v150
	v_mul_f32_e32 v151, v164, v151
	v_mul_f32_e32 v148, v148, v144
	v_mul_f32_e32 v149, v149, v145
	v_mul_f32_e32 v150, v150, v146
	v_mul_f32_e32 v151, v151, v147
	v_cvt_pk_bf16_f32 v202, v148, v149
	v_cvt_pk_bf16_f32 v203, v150, v151
	v_mul_f32_e32 v178, v163, v52
	v_mul_f32_e32 v179, v163, v54
	v_mul_f32_e32 v180, v163, v48
	v_mul_f32_e32 v181, v163, v50
	v_exp_f32_e32 v178, v178
	v_exp_f32_e32 v179, v179
	v_exp_f32_e32 v180, v180
	v_exp_f32_e32 v181, v181
	v_mul_f32_e32 v182, v52, v53
	v_mul_f32_e32 v183, v54, v55
	v_mul_f32_e32 v184, v48, v49
	v_mul_f32_e32 v185, v50, v51
	v_add_f32_e32 v178, 1.0, v178
	v_add_f32_e32 v179, 1.0, v179
	v_add_f32_e32 v180, 1.0, v180
	v_add_f32_e32 v181, 1.0, v181
	v_rcp_f32_e32 v178, v178
	v_rcp_f32_e32 v179, v179
	v_rcp_f32_e32 v180, v180
	v_rcp_f32_e32 v181, v181
	v_mul_f32_e32 v182, v164, v182
	v_mul_f32_e32 v183, v164, v183
	v_mul_f32_e32 v184, v164, v184
	v_mul_f32_e32 v185, v164, v185
	v_mul_f32_e32 v182, v182, v178
	v_mul_f32_e32 v183, v183, v179
	v_mul_f32_e32 v184, v184, v180
	v_mul_f32_e32 v185, v185, v181
	v_cvt_pk_bf16_f32 v206, v182, v183
	v_cvt_pk_bf16_f32 v207, v184, v185
	v_fmamk_f32 v162, v175, 0x3a800000, v160
	v_rsq_f32_e32 v162, v162
	s_nop 0
	v_mul_f32_e32 v163, 0xbfb8aa3b, v162
	v_mul_f32_e32 v164, v162, v162
	v_mul_f32_e32 v144, v163, v44
	v_mul_f32_e32 v145, v163, v46
	v_mul_f32_e32 v146, v163, v40
	v_mul_f32_e32 v147, v163, v42
	v_exp_f32_e32 v144, v144
	v_exp_f32_e32 v145, v145
	v_exp_f32_e32 v146, v146
	v_exp_f32_e32 v147, v147
	v_mul_f32_e32 v148, v44, v45
	v_mul_f32_e32 v149, v46, v47
	v_mul_f32_e32 v150, v40, v41
	v_mul_f32_e32 v151, v42, v43
	v_add_f32_e32 v144, 1.0, v144
	v_add_f32_e32 v145, 1.0, v145
	v_add_f32_e32 v146, 1.0, v146
	v_add_f32_e32 v147, 1.0, v147
	v_rcp_f32_e32 v144, v144
	v_rcp_f32_e32 v145, v145
	v_rcp_f32_e32 v146, v146
	v_rcp_f32_e32 v147, v147
	v_mul_f32_e32 v148, v164, v148
	v_mul_f32_e32 v149, v164, v149
	v_mul_f32_e32 v150, v164, v150
	v_mul_f32_e32 v151, v164, v151
	v_mul_f32_e32 v148, v148, v144
	v_mul_f32_e32 v149, v149, v145
	v_mul_f32_e32 v150, v150, v146
	v_mul_f32_e32 v151, v151, v147
	v_cvt_pk_bf16_f32 v204, v148, v149
	v_cvt_pk_bf16_f32 v205, v150, v151
	v_mul_f32_e32 v178, v163, v36
	v_mul_f32_e32 v179, v163, v38
	v_mul_f32_e32 v180, v163, v32
	v_mul_f32_e32 v181, v163, v34
	v_exp_f32_e32 v178, v178
	v_exp_f32_e32 v179, v179
	v_exp_f32_e32 v180, v180
	v_exp_f32_e32 v181, v181
	v_mul_f32_e32 v182, v36, v37
	v_mul_f32_e32 v183, v38, v39
	v_mul_f32_e32 v184, v32, v33
	v_mul_f32_e32 v185, v34, v35
	v_add_f32_e32 v178, 1.0, v178
	v_add_f32_e32 v179, 1.0, v179
	v_add_f32_e32 v180, 1.0, v180
	v_add_f32_e32 v181, 1.0, v181
	v_rcp_f32_e32 v178, v178
	v_rcp_f32_e32 v179, v179
	v_rcp_f32_e32 v180, v180
	v_rcp_f32_e32 v181, v181
	v_mul_f32_e32 v182, v164, v182
	v_mul_f32_e32 v183, v164, v183
	v_mul_f32_e32 v184, v164, v184
	v_mul_f32_e32 v185, v164, v185
	v_mul_f32_e32 v182, v182, v178
	v_mul_f32_e32 v183, v183, v179
	v_mul_f32_e32 v184, v184, v180
	v_mul_f32_e32 v185, v185, v181
	v_cvt_pk_bf16_f32 v208, v182, v183
	v_cvt_pk_bf16_f32 v209, v184, v185
	v_fmamk_f32 v162, v176, 0x3a800000, v160
	v_rsq_f32_e32 v162, v162
	s_nop 0
	v_mul_f32_e32 v163, 0xbfb8aa3b, v162
	v_mul_f32_e32 v164, v162, v162
	v_mul_f32_e32 v144, v163, v28
	v_mul_f32_e32 v145, v163, v30
	v_mul_f32_e32 v146, v163, v24
	v_mul_f32_e32 v147, v163, v26
	v_exp_f32_e32 v144, v144
	v_exp_f32_e32 v145, v145
	v_exp_f32_e32 v146, v146
	v_exp_f32_e32 v147, v147
	v_mul_f32_e32 v148, v28, v29
	v_mul_f32_e32 v149, v30, v31
	v_mul_f32_e32 v150, v24, v25
	v_mul_f32_e32 v151, v26, v27
	v_add_f32_e32 v144, 1.0, v144
	v_add_f32_e32 v145, 1.0, v145
	v_add_f32_e32 v146, 1.0, v146
	v_add_f32_e32 v147, 1.0, v147
	v_rcp_f32_e32 v144, v144
	v_rcp_f32_e32 v145, v145
	v_rcp_f32_e32 v146, v146
	v_rcp_f32_e32 v147, v147
	v_mul_f32_e32 v148, v164, v148
	v_mul_f32_e32 v149, v164, v149
	v_mul_f32_e32 v150, v164, v150
	v_mul_f32_e32 v151, v164, v151
	v_mul_f32_e32 v148, v148, v144
	v_mul_f32_e32 v149, v149, v145
	v_mul_f32_e32 v150, v150, v146
	v_mul_f32_e32 v151, v151, v147
	v_cvt_pk_bf16_f32 v210, v148, v149
	v_cvt_pk_bf16_f32 v211, v150, v151
	v_mul_f32_e32 v178, v163, v20
	v_mul_f32_e32 v179, v163, v22
	v_mul_f32_e32 v180, v163, v16
	v_mul_f32_e32 v181, v163, v18
	v_exp_f32_e32 v178, v178
	v_exp_f32_e32 v179, v179
	v_exp_f32_e32 v180, v180
	v_exp_f32_e32 v181, v181
	v_mul_f32_e32 v182, v20, v21
	v_mul_f32_e32 v183, v22, v23
	v_mul_f32_e32 v184, v16, v17
	v_mul_f32_e32 v185, v18, v19
	v_add_f32_e32 v178, 1.0, v178
	v_add_f32_e32 v179, 1.0, v179
	v_add_f32_e32 v180, 1.0, v180
	v_add_f32_e32 v181, 1.0, v181
	v_rcp_f32_e32 v178, v178
	v_rcp_f32_e32 v179, v179
	v_rcp_f32_e32 v180, v180
	v_rcp_f32_e32 v181, v181
	v_mul_f32_e32 v182, v164, v182
	v_mul_f32_e32 v183, v164, v183
	v_mul_f32_e32 v184, v164, v184
	v_mul_f32_e32 v185, v164, v185
	v_mul_f32_e32 v182, v182, v178
	v_mul_f32_e32 v183, v183, v179
	v_mul_f32_e32 v184, v184, v180
	v_mul_f32_e32 v185, v185, v181
	v_cvt_pk_bf16_f32 v216, v182, v183
	v_cvt_pk_bf16_f32 v217, v184, v185
	v_fmamk_f32 v162, v177, 0x3a800000, v160
	v_rsq_f32_e32 v162, v162
	s_nop 0
	v_mul_f32_e32 v163, 0xbfb8aa3b, v162
	v_mul_f32_e32 v164, v162, v162
	v_mul_f32_e32 v144, v163, v12
	v_mul_f32_e32 v145, v163, v14
	v_mul_f32_e32 v146, v163, v8
	v_mul_f32_e32 v147, v163, v10
	v_exp_f32_e32 v144, v144
	v_exp_f32_e32 v145, v145
	v_exp_f32_e32 v146, v146
	v_exp_f32_e32 v147, v147
	v_mul_f32_e32 v148, v12, v13
	v_mul_f32_e32 v149, v14, v15
	v_mul_f32_e32 v150, v8, v9
	v_mul_f32_e32 v151, v10, v11
	v_add_f32_e32 v144, 1.0, v144
	v_add_f32_e32 v145, 1.0, v145
	v_add_f32_e32 v146, 1.0, v146
	v_add_f32_e32 v147, 1.0, v147
	v_rcp_f32_e32 v144, v144
	v_rcp_f32_e32 v145, v145
	v_rcp_f32_e32 v146, v146
	v_rcp_f32_e32 v147, v147
	v_mul_f32_e32 v148, v164, v148
	v_mul_f32_e32 v149, v164, v149
	v_mul_f32_e32 v150, v164, v150
	v_mul_f32_e32 v151, v164, v151
	v_mul_f32_e32 v148, v148, v144
	v_mul_f32_e32 v149, v149, v145
	v_mul_f32_e32 v150, v150, v146
	v_mul_f32_e32 v151, v151, v147
	v_cvt_pk_bf16_f32 v212, v148, v149
	v_cvt_pk_bf16_f32 v213, v150, v151
	v_mul_f32_e32 v178, v163, v4
	v_mul_f32_e32 v179, v163, v6
	v_mul_f32_e32 v180, v163, v0
	v_mul_f32_e32 v181, v163, v2
	v_exp_f32_e32 v178, v178
	v_exp_f32_e32 v179, v179
	v_exp_f32_e32 v180, v180
	v_exp_f32_e32 v181, v181
	v_mul_f32_e32 v182, v4, v5
	v_mul_f32_e32 v183, v6, v7
	v_mul_f32_e32 v184, v0, v1
	v_mul_f32_e32 v185, v2, v3
	v_add_f32_e32 v178, 1.0, v178
	v_add_f32_e32 v179, 1.0, v179
	v_add_f32_e32 v180, 1.0, v180
	v_add_f32_e32 v181, 1.0, v181
	v_rcp_f32_e32 v178, v178
	v_rcp_f32_e32 v179, v179
	v_rcp_f32_e32 v180, v180
	v_rcp_f32_e32 v181, v181
	v_mul_f32_e32 v182, v164, v182
	v_mul_f32_e32 v183, v164, v183
	v_mul_f32_e32 v184, v164, v184
	v_mul_f32_e32 v185, v164, v185
	v_mul_f32_e32 v182, v182, v178
	v_mul_f32_e32 v183, v183, v179
	v_mul_f32_e32 v184, v184, v180
	v_mul_f32_e32 v185, v185, v181
	v_cvt_pk_bf16_f32 v218, v182, v183
	v_cvt_pk_bf16_f32 v219, v184, v185
	v_lshrrev_b32_e32 v162, 4, v214
	v_and_b32_e32 v162, 1, v162
	v_mul_u32_u24_e32 v162, 0x15ff8, v162
	v_mov_b32_e32 v163, 0
	v_lshl_add_u64 v[164:165], v[166:167], 0, v[162:163]
	s_mov_b64 s[64:65], 0x2c000
	s_mov_b64 s[66:67], 0x84000
	v_permlane16_swap_b32_e32 v186, v188
	v_permlane16_swap_b32_e32 v187, v189
	global_store_dwordx4 v[164:165], v[186:189], off
	v_permlane16_swap_b32_e32 v190, v192
	v_permlane16_swap_b32_e32 v191, v193
	global_store_dwordx4 v[164:165], v[190:193], off offset:128
	v_lshl_add_u64 v[164:165], v[164:165], 0, s[64:65]
	v_permlane16_swap_b32_e32 v194, v196
	v_permlane16_swap_b32_e32 v195, v197
	global_store_dwordx4 v[164:165], v[194:197], off
	v_permlane16_swap_b32_e32 v198, v200
	v_permlane16_swap_b32_e32 v199, v201
	global_store_dwordx4 v[164:165], v[198:201], off offset:128
	v_lshl_add_u64 v[164:165], v[164:165], 0, s[66:67]
	v_permlane16_swap_b32_e32 v202, v204
	v_permlane16_swap_b32_e32 v203, v205
	global_store_dwordx4 v[164:165], v[202:205], off
	v_permlane16_swap_b32_e32 v206, v208
	v_permlane16_swap_b32_e32 v207, v209
	global_store_dwordx4 v[164:165], v[206:209], off offset:128
	v_lshl_add_u64 v[164:165], v[164:165], 0, s[64:65]
	v_permlane16_swap_b32_e32 v210, v212
	v_permlane16_swap_b32_e32 v211, v213
	global_store_dwordx4 v[164:165], v[210:213], off
	v_permlane16_swap_b32_e32 v216, v218
	v_permlane16_swap_b32_e32 v217, v219
	global_store_dwordx4 v[164:165], v[216:219], off offset:128
	s_cbranch_vccnz .LBB0_886
	s_andn2_b64 vcc, exec, s[4:5]
	s_cbranch_vccnz .LBB0_885
	s_barrier
	s_branch .LBB0_885
